# hand-written scan loader loop (top-of-step DMA issue, DPP finisher) on top of v62
# baseline (speedup 1.0000x reference)
; #define LAS __attribute__((address_space(3)))
; __device__ __forceinline__ unsigned pk2(float lo, float hi) { return pg8::cvt_pk_bf16_v(lo, hi); }
; __device__ __forceinline__ float siluf(float x) { return x * __builtin_amdgcn_rcpf(1.0f + __expf(-x)); }
; __device__ __forceinline__ void unpack8(v4u w, float (&f)[8]) { f[0] = bflo(w.x); f[1] = bfhi(w.x); f[2] = bflo(w.y); f[3] = bfhi(w.y); f[4] = bflo(w.z); f[5] = bfhi(w.z); f[6] = bflo(w.w); f[7] = bfhi(w.w); }
; __device__ __forceinline__ void scan_prompt_wg(const Params& P, LAS unsigned char* lds, int s, int h, int wave, int lane) {
;     ...
;                 float o[16], zf[16]; { float t0[8], t1[8]; unpack8(*(const LAS v4u*)ot, t0); unpack8(*(const LAS v4u*)(ot + 16), t1);
; #pragma unroll
;                     for (int i = 0; i < 8; ++i) { o[i] = t0[i]; o[8 + i] = t1[i]; }
;                     unpack8(*(const LAS v4u*)zt, t0); unpack8(*(const LAS v4u*)(zt + 16), t1);
; #pragma unroll
;                     for (int i = 0; i < 8; ++i) { zf[i] = t0[i]; zf[8 + i] = t1[i]; } }
;                 float ss = 0.f;
; #pragma unroll
;                 for (int i = 0; i < 16; ++i) ss += o[i] * o[i];
;                 ss += __shfl_xor(ss, 1); ss += __shfl_xor(ss, 2);
;                 const float rstd = __builtin_amdgcn_rsqf(ss * (1.0f / 64.0f) + 1e-6f);
;                 float r[16];
; #pragma unroll
;                 for (int i = 0; i < 16; ++i) r[i] = o[i] * rstd * gg[i] * siluf(zf[i]);
;                 bf16* mp = Mr + (size_t)(n - 1) * 64 * 1024;
;                 v4u w0, w1; w0.x = pk2(r[0], r[1]); w0.y = pk2(r[2], r[3]); w0.z = pk2(r[4], r[5]); w0.w = pk2(r[6], r[7]); w1.x = pk2(r[8], r[9]); w1.y = pk2(r[10], r[11]); w1.z = pk2(r[12], r[13]); w1.w = pk2(r[14], r[15]);
;                 *(v4u*)mp = w0; *(v4u*)(mp + 8) = w1;
.Lld_noops:
	s_mov_b32 m0, s39
	s_cmp_eq_u32 s45, 0
	s_cbranch_scc1 .Lld_wait
	v_lshlrev_b32_e32 v34, 16, v31
	v_mul_f32_e32 v33, 0xbfb8aa3b, v34
	v_exp_f32_e32 v48, v33
	v_lshlrev_b32_e32 v62, 16, v29
	s_waitcnt lgkmcnt(2)
	v_lshlrev_b32_e32 v49, 16, v38
	v_add_f32_e32 v25, 1.0, v48
	v_rcp_f32_e32 v25, v25
	v_and_b32_e32 v48, 0xffff0000, v38
	v_and_b32_e32 v63, 0xffff0000, v29
	v_mul_f32_e32 v29, 0xbfb8aa3b, v63
	v_mul_f32_e32 v38, v25, v34
	v_mul_f32_e32 v25, 0xbfb8aa3b, v62
	v_exp_f32_e32 v25, v25
	v_exp_f32_e32 v29, v29
	v_lshlrev_b32_e32 v68, 16, v37
	v_and_b32_e32 v69, 0xffff0000, v37
	v_add_f32_e32 v25, 1.0, v25
	v_rcp_f32_e32 v66, v25
	v_add_f32_e32 v25, 1.0, v29
	v_rcp_f32_e32 v67, v25
	v_and_b32_e32 v37, 0xffff0000, v28
	v_and_b32_e32 v60, 0xffff0000, v31
	s_waitcnt lgkmcnt(1)
	v_lshlrev_b32_e32 v74, 16, v43
	v_pk_mul_f32 v[62:63], v[66:67], v[62:63]
	v_lshlrev_b32_e32 v66, 16, v36
	v_and_b32_e32 v67, 0xffff0000, v36
	v_lshlrev_b32_e32 v36, 16, v28
	v_mul_f32_e32 v25, 0xbfb8aa3b, v36
	v_exp_f32_e32 v25, v25
	v_mul_f32_e32 v28, 0xbfb8aa3b, v37
	v_exp_f32_e32 v31, v28
	v_and_b32_e32 v75, 0xffff0000, v43
	v_add_f32_e32 v25, 1.0, v25
	v_rcp_f32_e32 v72, v25
	v_add_f32_e32 v25, 1.0, v31
	v_rcp_f32_e32 v73, v25
	v_mul_f32_e32 v25, 0xbfb8aa3b, v74
	v_exp_f32_e32 v25, v25
	v_mul_f32_e32 v31, 0xbfb8aa3b, v75
	v_exp_f32_e32 v31, v31
	v_pk_mul_f32 v[36:37], v[72:73], v[36:37]
	v_add_f32_e32 v25, 1.0, v25
	v_rcp_f32_e32 v72, v25
	v_add_f32_e32 v25, 1.0, v31
	v_rcp_f32_e32 v73, v25
	s_waitcnt lgkmcnt(0)
	v_lshlrev_b32_e32 v76, 16, v47
	v_and_b32_e32 v77, 0xffff0000, v47
	v_and_b32_e32 v47, 0xffff0000, v42
	v_pk_mul_f32 v[72:73], v[72:73], v[74:75]
	v_lshlrev_b32_e32 v74, 16, v46
	v_and_b32_e32 v75, 0xffff0000, v46
	v_lshlrev_b32_e32 v46, 16, v42
	v_mul_f32_e32 v25, 0xbfb8aa3b, v46
	v_exp_f32_e32 v25, v25
	v_mul_f32_e32 v31, 0xbfb8aa3b, v47
	v_exp_f32_e32 v31, v31
	v_lshlrev_b32_e32 v84, 16, v41
	v_add_f32_e32 v25, 1.0, v25
	v_rcp_f32_e32 v80, v25
	v_add_f32_e32 v25, 1.0, v31
	v_rcp_f32_e32 v81, v25
	v_and_b32_e32 v85, 0xffff0000, v41
	v_mul_f32_e32 v25, 0xbfb8aa3b, v84
	v_exp_f32_e32 v25, v25
	v_mul_f32_e32 v31, 0xbfb8aa3b, v85
	v_exp_f32_e32 v31, v31
	v_lshlrev_b32_e32 v90, 16, v44
	v_add_f32_e32 v25, 1.0, v25
	v_and_b32_e32 v91, 0xffff0000, v44
	v_lshlrev_b32_e32 v82, 16, v45
	v_and_b32_e32 v83, 0xffff0000, v45
	v_rcp_f32_e32 v88, v25
	v_add_f32_e32 v25, 1.0, v31
	v_lshlrev_b32_e32 v44, 16, v40
	v_and_b32_e32 v45, 0xffff0000, v40
	v_pk_mul_f32 v[40:41], v[90:91], v[90:91]
	v_pk_mul_f32 v[86:87], v[82:83], v[82:83]
	v_rcp_f32_e32 v89, v25
	v_add_f32_e32 v25, v40, v41
	v_add_f32_e32 v25, v86, v25
	v_pk_mul_f32 v[42:43], v[74:75], v[74:75]
	v_add_f32_e32 v25, v87, v25
	v_add_f32_e32 v25, v42, v25
	v_pk_mul_f32 v[78:79], v[76:77], v[76:77]
	v_add_f32_e32 v25, v43, v25
	v_add_f32_e32 v25, v78, v25
	v_pk_mul_f32 v[28:29], v[66:67], v[66:67]
	v_add_f32_e32 v25, v79, v25
	v_add_f32_e32 v25, v28, v25
	v_pk_mul_f32 v[70:71], v[68:69], v[68:69]
	v_add_f32_e32 v25, v29, v25
	v_add_f32_e32 v25, v70, v25
	v_pk_mul_f32 v[50:51], v[48:49], v[48:49]
	v_and_b32_e32 v61, 0xffff0000, v39
	v_add_f32_e32 v25, v71, v25
	v_lshlrev_b32_e32 v33, 16, v39
	v_mov_b32_e32 v32, v61
	v_add_f32_e32 v25, v51, v25
	v_pk_mul_f32 v[64:65], v[32:33], v[32:33]
	v_add_f32_e32 v25, v50, v25
	v_add_f32_e32 v25, v65, v25
	v_add_f32_e32 v25, v64, v25
	v_lshlrev_b32_e32 v50, 16, v30
	v_and_b32_e32 v51, 0xffff0000, v30
	v_mul_f32_e32 v29, 0xbfb8aa3b, v44
	v_mul_f32_e32 v31, 0xbfb8aa3b, v45
	v_add_f32_dpp v25, v25, v25 quad_perm:[1,0,3,2] row_mask:0xf bank_mask:0xf
	v_mul_f32_e32 v30, 0xbfb8aa3b, v51
	v_exp_f32_e32 v29, v29
	v_exp_f32_e32 v31, v31
	v_exp_f32_e32 v34, v30
	v_add_f32_dpp v25, v25, v25 quad_perm:[2,3,0,1] row_mask:0xf bank_mask:0xf
	v_fmamk_f32 v25, v25, 0x3c800000, v24
	v_rsq_f32_e32 v32, v25
	v_mul_f32_e32 v25, 0xbfb8aa3b, v50
	v_exp_f32_e32 v25, v25
	v_pk_mul_f32 v[40:41], v[80:81], v[46:47]
	v_pk_mul_f32 v[46:47], v[32:33], v[66:67] op_sel_hi:[0,1]
	v_pk_mul_f32 v[46:47], v[10:11], v[46:47]
	v_add_f32_e32 v25, 1.0, v25
	v_pk_mul_f32 v[36:37], v[36:37], v[46:47]
	v_pk_mul_f32 v[46:47], v[32:33], v[68:69] op_sel_hi:[0,1]
	v_add_f32_e32 v28, 1.0, v29
	v_add_f32_e32 v29, 1.0, v31
	v_pk_mul_f32 v[30:31], v[12:13], v[46:47]
	v_rcp_f32_e32 v46, v25
	v_add_f32_e32 v25, 1.0, v34
	v_rcp_f32_e32 v28, v28
	v_rcp_f32_e32 v29, v29
	v_rcp_f32_e32 v47, v25
	v_mul_f32_e32 v25, 0xbfb8aa3b, v60
	v_exp_f32_e32 v25, v25
	v_pk_mul_f32 v[28:29], v[28:29], v[44:45]
	v_pk_mul_f32 v[44:45], v[32:33], v[90:91] op_sel_hi:[0,1]
	v_pk_mul_f32 v[44:45], v[2:3], v[44:45]
	v_add_f32_e32 v25, 1.0, v25
	v_pk_mul_f32 v[28:29], v[28:29], v[44:45]
	v_pk_mul_f32 v[44:45], v[32:33], v[82:83] op_sel_hi:[0,1]
	v_pk_mul_f32 v[62:63], v[62:63], v[30:31]
	v_pk_mul_f32 v[30:31], v[46:47], v[50:51]
	v_pk_mul_f32 v[46:47], v[32:33], v[48:49] op_sel_hi:[0,1]
	v_rcp_f32_e32 v48, v25
	v_pk_mul_f32 v[42:43], v[88:89], v[84:85]
	v_pk_mul_f32 v[44:45], v[4:5], v[44:45]
	v_pk_mul_f32 v[46:47], v[20:21], v[46:47]
	v_pk_mul_f32 v[42:43], v[42:43], v[44:45]
	v_pk_mul_f32 v[44:45], v[32:33], v[74:75] op_sel_hi:[0,1]
	v_pk_mul_f32 v[44:45], v[6:7], v[44:45]
	v_mov_b32_e32 v49, v32
	v_pk_mul_f32 v[40:41], v[40:41], v[44:45]
	v_pk_mul_f32 v[44:45], v[32:33], v[76:77] op_sel_hi:[0,1]
	v_pk_mul_f32 v[46:47], v[30:31], v[46:47] op_sel:[0,1] op_sel_hi:[1,0]
	v_mul_f32_e32 v30, v32, v33
	v_pk_mul_f32 v[32:33], v[48:49], v[60:61]
	v_pk_mul_f32 v[44:45], v[8:9], v[44:45]
	v_mov_b32_e32 v31, v33
	s_lshl_b64 s[20:21], s[10:11], 17
	v_pk_mul_f32 v[44:45], v[72:73], v[44:45]
	v_pk_mul_f32 v[30:31], v[16:17], v[30:31]
	v_mov_b32_e32 v39, v32
	v_pk_mul_f32 v[32:33], v[38:39], v[30:31]
	v_lshl_add_u64 v[48:49], v[14:15], 0, s[20:21]
	v_readlane_b32 s96, v247, 24
	v_cvt_pk_bf16_f32 v28, v28, v29
	v_cvt_pk_bf16_f32 v29, v42, v43
	v_cvt_pk_bf16_f32 v30, v40, v41
	v_cvt_pk_bf16_f32 v31, v44, v45
	v_cvt_pk_bf16_f32 v36, v36, v37
	v_cvt_pk_bf16_f32 v37, v62, v63
	v_cvt_pk_bf16_f32 v38, v46, v47
	v_cvt_pk_bf16_f32 v39, v32, v33
	global_store_dwordx4 v[48:49], v[28:31], off
	global_store_dwordx4 v[48:49], v[36:39], off offset:16
